# pvprio_s + in-proj row-scale pre-pass batched into one memory round trip (up to 4 units' SSX rows loaded before any arithmetic; same sum association and sqrt/div sequence)
# speedup vs baseline: 1.0076x; 1.0040x over previous
; #define PG8_STAGE(bufoff, gbase, voff) glds16s2((voff)[0], (voff)[1], (const void*)(gbase), ldsn + (unsigned)(bufoff))
; template <class Epi, bool ALIGN_EPI, bool EARLY_DRAIN = true, class Pre = NoPre>
; __device__ __forceinline__ void gemm_phase(LAS unsigned char* lds, const Gemm g, const StaticOrder& S, const Epi& E, int wv, const Pre& pre = Pre()) {
;     int tid_ = wv * 64 + lane_now(); asm volatile("" : "+v"(tid_));
;     const int tid = tid_, wid = __builtin_amdgcn_readfirstlane(tid >> 6), lane = tid & 63, wr = wid >> 2, wc = wid & 3, fr = lane & 15, fq = lane >> 4;
;     const int K = g.K, nt = K / BK;
;     unsigned voffA[2], voffB[2];
; #pragma unroll
;     for (int i = 0; i < 2; ++i) { int R, C; stage_rc(tid * 16 + i * 8192, R, C); const int Rb = (R & ~31) + perm32(R & 31);
;         const int Ra = g.amap ? (126 * (R >> 6) + 8 * (R & 15) + ((R >> 4) & 3)) : R;
;         voffA[i] = (unsigned)(Ra * K + C) * 2u; voffB[i] = (unsigned)(Rb * K + C) * 2u; }
;     const size_t kstep = (size_t)(BK * 2);
;     const size_t ahs = (size_t)g.a_hstep, bhs = (size_t)g.b_hstep;
;     const unsigned ldsw = (unsigned)wid * 1024u; const unsigned ldsn = (unsigned)(uintptr_t)lds + ldsw;
;     const int aoff = lds_byte(wr * 64 + fr, fq * 8), boff = lds_byte(wc * 32 + fr, fq * 8);
;     ...
;     Unit cur, nxt; int ui = 0; bool fresh = false;
;     if (!S.next(0, cur)) return;
;     f32x4 acc[2][2][4][2];
; #pragma unroll
;     for (int a = 0; a < 2; ++a)
; #pragma unroll
;         for (int b = 0; b < 2; ++b)
; #pragma unroll
;             for (int m = 0; m < 4; ++m)
; #pragma unroll
;                 for (int n = 0; n < 2; ++n) acc[a][b][m][n] = (f32x4){0.f, 0.f, 0.f, 0.f};
;     bf16x8 At[4][2], B0[2][2], B1[2][2];
;     const char* cA = g.A + (size_t)cur.pm * g.a_tstep + (size_t)(cur.pm >> 6) * g.a_pad; const char* cB = g.Bt + (size_t)cur.pn * g.b_tstep;
;     if constexpr (Epi::HOOK) E.unit_start(cur, ui, wid, lane);
;     PG8_STAGE(PG8_SB(0, 0), cB, voffB); PG8_STAGE(PG8_SB(0, 1), cB + bhs, voffB); PG8_STAGE(PG8_SA(0, 0), cA, voffA); PG8_STAGE(PG8_SA(0, 1), cA + ahs, voffA);
; __global__ void __launch_bounds__(NWAVES * 64, 2) fwd_kernel(Args args) {
;     ...
;             auto pre = [&]() __attribute__((always_inline))
;             { pg8::Unit u; for (int i = wave >> 2; S.next(i, u); i += 2)       { const int row = tid & 255; const float* p = SSX + (size_t)(u.pm * 256 + row) * 16;
.LBB0_155:
	s_mul_i32 s0, s76, 5
	v_writelane_b32 v255, s0, 6
	s_add_i32 s0, s0, 1
	s_mul_i32 s4, s76, 0x1700000
	v_readlane_b32 s5, v252, 37
	s_add_u32 s4, s5, s4
	v_readlane_b32 s5, v252, 38
	s_addc_u32 s9, s5, 0
	v_readlane_b32 s14, v252, 3
	v_readlane_b32 s15, v252, 4
	s_cmp_le_i32 s14, s0
	s_cselect_b64 s[12:13], -1, 0
	s_cmp_lt_i32 s0, s15
	s_cselect_b64 s[16:17], -1, 0
	s_and_b64 s[16:17], s[12:13], s[16:17]
	s_andn2_b64 vcc, exec, s[16:17]
	s_cbranch_vccnz .LBB0_190
	v_readlane_b32 s0, v252, 43
	v_mbcnt_lo_u32_b32 v0, -1, 0
	v_mbcnt_hi_u32_b32 v0, -1, v0
	v_readlane_b32 s12, v252, 44
	v_readlane_b32 s13, v252, 45
	v_add_u32_e32 v3, s0, v0
	v_mbcnt_lo_u32_b32 v0, -1, 0
	v_mbcnt_hi_u32_b32 v0, -1, v0
	s_andn2_b64 vcc, exec, s[12:13]
	v_add_u32_e32 v2, s0, v0
	s_nop 0
	v_readfirstlane_b32 s0, v2
	s_cbranch_vccnz .LBB0_190
	v_bfe_i32 v5, v2, 27, 1
	v_lshlrev_b32_e32 v4, 4, v2
	v_lshrrev_b32_e32 v5, 22, v5
	v_add_u32_e32 v5, v4, v5
	v_and_b32_e32 v5, 0xfffffc00, v5
	v_sub_u32_e32 v5, v4, v5
	v_ashrrev_i32_e32 v0, 31, v2
	v_lshrrev_b32_e32 v6, 4, v5
	v_lshrrev_b32_e32 v0, 26, v0
	v_bitop3_b32 v5, v6, v5, 32 bitop3:0x6c
	v_add_u32_e32 v0, v2, v0
	v_ashrrev_i32_e32 v7, 31, v5
	v_ashrrev_i32_e32 v0, 6, v0
	v_lshrrev_b32_e32 v7, 26, v7
	v_lshlrev_b32_e32 v6, 3, v0
	v_add_u32_e32 v7, v5, v7
	v_and_b32_e32 v6, -16, v6
	v_ashrrev_i32_e32 v8, 6, v7
	v_and_b32_e32 v7, 0xc0, v7
	v_add_u32_e32 v6, v8, v6
	v_sub_u32_e32 v5, v5, v7
	v_lshlrev_b32_e32 v0, 5, v0
	v_ashrrev_i16_sdwa v5, v248, sext(v5) dst_sel:DWORD dst_unused:UNUSED_PAD src0_sel:DWORD src1_sel:BYTE_0
	v_lshlrev_b32_e32 v7, 1, v6
	v_lshrrev_b32_e32 v9, 2, v6
	v_and_b32_e32 v8, 3, v8
	s_mov_b32 s5, 0x1fffe0
	v_and_b32_e32 v0, 32, v0
	v_bfe_i32 v5, v5, 0, 16
	v_and_b32_e32 v7, 24, v7
	v_and_b32_e32 v9, 4, v9
	v_and_or_b32 v8, v6, s5, v8
	v_or3_b32 v7, v8, v9, v7
	v_add_lshl_u32 v5, v0, v5, 1
	v_add_u32_e32 v4, 0x2000, v4
	v_lshl_add_u32 v0, v6, 11, v5
	v_lshl_add_u32 v230, v7, 11, v5
	v_ashrrev_i32_e32 v5, 31, v4
	v_lshrrev_b32_e32 v5, 22, v5
	v_add_u32_e32 v5, v4, v5
	v_ashrrev_i32_e32 v5, 10, v5
	v_mul_i32_i24_e32 v6, 0x400, v5
	v_sub_u32_e32 v4, v4, v6
	v_lshrrev_b32_e32 v6, 4, v4
	v_bitop3_b32 v4, v6, v4, 32 bitop3:0x6c
	v_ashrrev_i32_e32 v7, 31, v4
	v_lshrrev_b32_e32 v7, 26, v7
	v_lshlrev_b32_e32 v6, 3, v5
	v_add_u32_e32 v7, v4, v7
	v_and_b32_e32 v6, -16, v6
	v_ashrrev_i32_e32 v8, 6, v7
	v_and_b32_e32 v7, 0xc0, v7
	s_ashr_i32 s23, s0, 6
	v_add_u32_e32 v6, v8, v6
	v_sub_u32_e32 v4, v4, v7
	v_and_b32_e32 v8, 3, v8
	v_lshlrev_b32_e32 v5, 5, v5
	v_ashrrev_i16_sdwa v4, v248, sext(v4) dst_sel:DWORD dst_unused:UNUSED_PAD src0_sel:DWORD src1_sel:BYTE_0
	v_lshlrev_b32_e32 v7, 1, v6
	v_lshrrev_b32_e32 v9, 2, v6
	v_and_or_b32 v8, v6, s5, v8
	s_lshl_b32 s5, s23, 10
	v_and_b32_e32 v5, 32, v5
	v_bfe_i32 v4, v4, 0, 16
	v_and_b32_e32 v7, 24, v7
	v_and_b32_e32 v9, 4, v9
	s_add_i32 s5, s5, 0
	v_readlane_b32 s12, v254, 22
	v_or3_b32 v7, v8, v9, v7
	v_add_lshl_u32 v4, v5, v4, 1
	v_readlane_b32 s13, v254, 23
	s_add_u32 s68, s4, s12
	v_lshl_add_u32 v232, v7, 11, v4
	s_addc_u32 s69, s9, s13
	s_add_i32 s10, s5, 0x10000
	s_mov_b32 m0, s10
	s_nop 0
	global_load_lds_dwordx4 v230, s[68:69]
	s_add_u32 m0, m0, 0x2000
	s_nop 0
	global_load_lds_dwordx4 v232, s[68:69]
	s_add_u32 s18, s68, 0x40000
	v_readlane_b32 s14, v254, 26
	s_addc_u32 s19, s69, 0
	s_add_i32 s12, s5, 0x14000
	s_mov_b32 m0, s12
	s_nop 0
	global_load_lds_dwordx4 v230, s[18:19]
	s_add_u32 m0, m0, 0x2000
	s_nop 0
	global_load_lds_dwordx4 v232, s[18:19]
	v_readlane_b32 s15, v254, 27
	v_lshl_add_u32 v231, v6, 11, v4
	s_mov_b32 m0, s5
	s_nop 0
	global_load_lds_dwordx4 v0, s[14:15]
	s_add_u32 m0, m0, 0x2000
	s_nop 0
	global_load_lds_dwordx4 v231, s[14:15]
	v_readlane_b32 s14, v254, 24
	s_add_i32 s13, s5, 0x4000
	v_readlane_b32 s15, v254, 25
	s_mov_b32 m0, s13
	s_nop 0
	global_load_lds_dwordx4 v0, s[14:15]
	s_add_u32 m0, m0, 0x2000
	s_nop 0
	global_load_lds_dwordx4 v231, s[14:15]
	v_and_b32_e32 v3, 0xff, v3
	v_readlane_b32 s14, v254, 51
	v_readlane_b32 s18, v254, 48
	v_readlane_b32 s19, v254, 49
	v_lshl_add_u32 v4, v3, 2, s14
	s_mov_b32 s20, 0
	s_cmpk_gt_u32 s18, 0x6bf
	s_cbranch_scc1 .Lipre_issued
	s_and_b32 s14, s18, 7
	s_lshr_b32 s15, s18, 3
	s_mulk_i32 s14, 0xd8
	s_add_i32 s14, s14, s15
	s_mul_hi_u32 s15, s14, 0x38e38e39
	s_lshr_b32 s15, s15, 4
	s_mul_i32 s22, s15, 0x48
	s_sub_i32 s14, s14, s22
	s_and_b32 s14, s14, 7
	s_lshl_b32 s15, s15, 3
	s_add_i32 s22, s15, s14
	v_lshl_or_b32 v6, s22, 8, v3
	v_lshlrev_b32_e32 v6, 6, v6
	global_load_dwordx4 v[22:25], v6, s[28:29]
	global_load_dwordx4 v[26:29], v6, s[28:29] offset:16
	global_load_dwordx4 v[30:33], v6, s[28:29] offset:32
	global_load_dwordx4 v[34:37], v6, s[28:29] offset:48
	s_add_i32 s20, s20, 1
	s_add_u32 s18, s18, s74
	s_cmpk_gt_u32 s18, 0x6bf
	s_cbranch_scc1 .Lipre_issued
	s_and_b32 s14, s18, 7
	s_lshr_b32 s15, s18, 3
	s_mulk_i32 s14, 0xd8
	s_add_i32 s14, s14, s15
	s_mul_hi_u32 s15, s14, 0x38e38e39
	s_lshr_b32 s15, s15, 4
	s_mul_i32 s22, s15, 0x48
	s_sub_i32 s14, s14, s22
	s_and_b32 s14, s14, 7
	s_lshl_b32 s15, s15, 3
	s_add_i32 s22, s15, s14
	v_lshl_or_b32 v6, s22, 8, v3
	v_lshlrev_b32_e32 v6, 6, v6
	global_load_dwordx4 v[38:41], v6, s[28:29]
	global_load_dwordx4 v[42:45], v6, s[28:29] offset:16
	global_load_dwordx4 v[46:49], v6, s[28:29] offset:32
	global_load_dwordx4 v[50:53], v6, s[28:29] offset:48
	s_add_i32 s20, s20, 1
	s_add_u32 s18, s18, s74
	s_cmpk_gt_u32 s18, 0x6bf
	s_cbranch_scc1 .Lipre_issued
	s_and_b32 s14, s18, 7
	s_lshr_b32 s15, s18, 3
	s_mulk_i32 s14, 0xd8
	s_add_i32 s14, s14, s15
	s_mul_hi_u32 s15, s14, 0x38e38e39
	s_lshr_b32 s15, s15, 4
	s_mul_i32 s22, s15, 0x48
	s_sub_i32 s14, s14, s22
	s_and_b32 s14, s14, 7
	s_lshl_b32 s15, s15, 3
	s_add_i32 s22, s15, s14
	v_lshl_or_b32 v6, s22, 8, v3
	v_lshlrev_b32_e32 v6, 6, v6
	global_load_dwordx4 v[54:57], v6, s[28:29]
	global_load_dwordx4 v[58:61], v6, s[28:29] offset:16
	global_load_dwordx4 v[62:65], v6, s[28:29] offset:32
	global_load_dwordx4 v[66:69], v6, s[28:29] offset:48
	s_add_i32 s20, s20, 1
	s_add_u32 s18, s18, s74
	s_cmpk_gt_u32 s18, 0x6bf
	s_cbranch_scc1 .Lipre_issued
	s_and_b32 s14, s18, 7
	s_lshr_b32 s15, s18, 3
	s_mulk_i32 s14, 0xd8
	s_add_i32 s14, s14, s15
	s_mul_hi_u32 s15, s14, 0x38e38e39
	s_lshr_b32 s15, s15, 4
	s_mul_i32 s22, s15, 0x48
	s_sub_i32 s14, s14, s22
	s_and_b32 s14, s14, 7
	s_lshl_b32 s15, s15, 3
	s_add_i32 s22, s15, s14
	v_lshl_or_b32 v6, s22, 8, v3
	v_lshlrev_b32_e32 v6, 6, v6
	global_load_dwordx4 v[70:73], v6, s[28:29]
	global_load_dwordx4 v[74:77], v6, s[28:29] offset:16
	global_load_dwordx4 v[78:81], v6, s[28:29] offset:32
	global_load_dwordx4 v[82:85], v6, s[28:29] offset:48
	s_add_i32 s20, s20, 1
	s_add_u32 s18, s18, s74
; __global__ void __launch_bounds__(NWAVES * 64, 2) fwd_kernel(Args args) {
;     ...
;             { pg8::Unit u; for (int i = wave >> 2; S.next(i, u); i += 2)       { const int row = tid & 255; const float* p = SSX + (size_t)(u.pm * 256 + row) * 16;
;                 const f32x4 a = *(const f32x4*)p, b = *(const f32x4*)(p + 4), c = *(const f32x4*)(p + 8), d = *(const f32x4*)(p + 12);
;                 const float s = ((a[0] + a[1]) + (a[2] + a[3])) + ((b[0] + b[1]) + (b[2] + b[3])) + ((c[0] + c[1]) + (c[2] + c[3])) + ((d[0] + d[1]) + (d[2] + d[3]));
;                 tab[i * 256 + row] = 1.0f / sqrtf(s * (1.0f / D) + EPS); } }
.Lipre_issued:
	s_waitcnt vmcnt(0)
	s_mov_b32 s14, 0xf800000
	s_cmp_le_u32 s20, 0
	s_cbranch_scc1 .Lipre_done
	v_add_f32_e32 v22, v22, v23
	v_add_f32_e32 v24, v24, v25
	v_add_f32_e32 v22, v22, v24
	v_add_f32_e32 v26, v26, v27
	v_add_f32_e32 v28, v28, v29
	v_add_f32_e32 v26, v26, v28
	v_add_f32_e32 v30, v30, v31
	v_add_f32_e32 v32, v32, v33
	v_add_f32_e32 v30, v30, v32
	v_add_f32_e32 v34, v34, v35
	v_add_f32_e32 v36, v36, v37
	v_add_f32_e32 v34, v34, v36
	v_add_f32_e32 v22, v22, v26
	v_add_f32_e32 v22, v22, v30
	v_add_f32_e32 v5, v22, v34
	v_fmamk_f32 v5, v5, 0x3a800000, v251
	v_mul_f32_e32 v6, 0x4f800000, v5
	v_cmp_gt_f32_e32 vcc, s14, v5
	s_nop 1
	v_cndmask_b32_e32 v5, v5, v6, vcc
	v_sqrt_f32_e32 v6, v5
	s_nop 0
	v_add_u32_e32 v7, -1, v6
	v_add_u32_e32 v8, 1, v6
	v_fma_f32 v9, -v7, v6, v5
	v_fma_f32 v10, -v8, v6, v5
	v_cmp_ge_f32_e64 s[34:35], 0, v9
	s_nop 1
	v_cndmask_b32_e64 v6, v6, v7, s[34:35]
	v_cmp_lt_f32_e64 s[34:35], 0, v10
	s_nop 1
	v_cndmask_b32_e64 v6, v6, v8, s[34:35]
	v_mul_f32_e32 v7, 0x37800000, v6
	v_cndmask_b32_e32 v6, v6, v7, vcc
	v_cmp_class_f32_e32 vcc, v5, v247
	s_nop 1
	v_cndmask_b32_e32 v5, v6, v5, vcc
	v_div_scale_f32 v6, s[24:25], v5, v5, 1.0
	v_rcp_f32_e32 v7, v6
	v_div_scale_f32 v8, vcc, 1.0, v5, 1.0
	v_fma_f32 v9, -v6, v7, 1.0
	v_fmac_f32_e32 v7, v9, v7
	v_mul_f32_e32 v9, v8, v7
	v_fma_f32 v10, -v6, v9, v8
	v_fmac_f32_e32 v9, v10, v7
	v_fma_f32 v6, -v6, v9, v8
	v_div_fmas_f32 v6, v6, v7, v9
	v_div_fixup_f32 v5, v6, v5, 1.0
	ds_write_b32 v4, v5
	s_cmp_le_u32 s20, 1
	s_cbranch_scc1 .Lipre_done
	v_add_f32_e32 v38, v38, v39
	v_add_f32_e32 v40, v40, v41
	v_add_f32_e32 v38, v38, v40
	v_add_f32_e32 v42, v42, v43
	v_add_f32_e32 v44, v44, v45
	v_add_f32_e32 v42, v42, v44
	v_add_f32_e32 v46, v46, v47
	v_add_f32_e32 v48, v48, v49
	v_add_f32_e32 v46, v46, v48
	v_add_f32_e32 v50, v50, v51
	v_add_f32_e32 v52, v52, v53
	v_add_f32_e32 v50, v50, v52
	v_add_f32_e32 v38, v38, v42
	v_add_f32_e32 v38, v38, v46
	v_add_f32_e32 v5, v38, v50
	v_fmamk_f32 v5, v5, 0x3a800000, v251
	v_mul_f32_e32 v6, 0x4f800000, v5
	v_cmp_gt_f32_e32 vcc, s14, v5
	s_nop 1
	v_cndmask_b32_e32 v5, v5, v6, vcc
	v_sqrt_f32_e32 v6, v5
	s_nop 0
	v_add_u32_e32 v7, -1, v6
	v_add_u32_e32 v8, 1, v6
	v_fma_f32 v9, -v7, v6, v5
	v_fma_f32 v10, -v8, v6, v5
	v_cmp_ge_f32_e64 s[34:35], 0, v9
	s_nop 1
	v_cndmask_b32_e64 v6, v6, v7, s[34:35]
	v_cmp_lt_f32_e64 s[34:35], 0, v10
	s_nop 1
	v_cndmask_b32_e64 v6, v6, v8, s[34:35]
	v_mul_f32_e32 v7, 0x37800000, v6
	v_cndmask_b32_e32 v6, v6, v7, vcc
	v_cmp_class_f32_e32 vcc, v5, v247
	s_nop 1
	v_cndmask_b32_e32 v5, v6, v5, vcc
	v_div_scale_f32 v6, s[24:25], v5, v5, 1.0
	v_rcp_f32_e32 v7, v6
	v_div_scale_f32 v8, vcc, 1.0, v5, 1.0
	v_fma_f32 v9, -v6, v7, 1.0
	v_fmac_f32_e32 v7, v9, v7
	v_mul_f32_e32 v9, v8, v7
	v_fma_f32 v10, -v6, v9, v8
	v_fmac_f32_e32 v9, v10, v7
	v_fma_f32 v6, -v6, v9, v8
	v_div_fmas_f32 v6, v6, v7, v9
	v_div_fixup_f32 v5, v6, v5, 1.0
	ds_write_b32 v4, v5 offset:2048
	s_cmp_le_u32 s20, 2
	s_cbranch_scc1 .Lipre_done
	v_add_f32_e32 v54, v54, v55
	v_add_f32_e32 v56, v56, v57
	v_add_f32_e32 v54, v54, v56
	v_add_f32_e32 v58, v58, v59
	v_add_f32_e32 v60, v60, v61
	v_add_f32_e32 v58, v58, v60
	v_add_f32_e32 v62, v62, v63
	v_add_f32_e32 v64, v64, v65
	v_add_f32_e32 v62, v62, v64
	v_add_f32_e32 v66, v66, v67
	v_add_f32_e32 v68, v68, v69
	v_add_f32_e32 v66, v66, v68
	v_add_f32_e32 v54, v54, v58
	v_add_f32_e32 v54, v54, v62
	v_add_f32_e32 v5, v54, v66
	v_fmamk_f32 v5, v5, 0x3a800000, v251
	v_mul_f32_e32 v6, 0x4f800000, v5
	v_cmp_gt_f32_e32 vcc, s14, v5
	s_nop 1
	v_cndmask_b32_e32 v5, v5, v6, vcc
	v_sqrt_f32_e32 v6, v5
	s_nop 0
	v_add_u32_e32 v7, -1, v6
	v_add_u32_e32 v8, 1, v6
	v_fma_f32 v9, -v7, v6, v5
	v_fma_f32 v10, -v8, v6, v5
	v_cmp_ge_f32_e64 s[34:35], 0, v9
	s_nop 1
	v_cndmask_b32_e64 v6, v6, v7, s[34:35]
	v_cmp_lt_f32_e64 s[34:35], 0, v10
	s_nop 1
	v_cndmask_b32_e64 v6, v6, v8, s[34:35]
	v_mul_f32_e32 v7, 0x37800000, v6
	v_cndmask_b32_e32 v6, v6, v7, vcc
	v_cmp_class_f32_e32 vcc, v5, v247
	s_nop 1
	v_cndmask_b32_e32 v5, v6, v5, vcc
	v_div_scale_f32 v6, s[24:25], v5, v5, 1.0
	v_rcp_f32_e32 v7, v6
	v_div_scale_f32 v8, vcc, 1.0, v5, 1.0
	v_fma_f32 v9, -v6, v7, 1.0
	v_fmac_f32_e32 v7, v9, v7
	v_mul_f32_e32 v9, v8, v7
	v_fma_f32 v10, -v6, v9, v8
	v_fmac_f32_e32 v9, v10, v7
	v_fma_f32 v6, -v6, v9, v8
	v_div_fmas_f32 v6, v6, v7, v9
	v_div_fixup_f32 v5, v6, v5, 1.0
	ds_write_b32 v4, v5 offset:4096
	s_cmp_le_u32 s20, 3
	s_cbranch_scc1 .Lipre_done
	v_add_f32_e32 v70, v70, v71
	v_add_f32_e32 v72, v72, v73
	v_add_f32_e32 v70, v70, v72
	v_add_f32_e32 v74, v74, v75
	v_add_f32_e32 v76, v76, v77
	v_add_f32_e32 v74, v74, v76
	v_add_f32_e32 v78, v78, v79
	v_add_f32_e32 v80, v80, v81
	v_add_f32_e32 v78, v78, v80
	v_add_f32_e32 v82, v82, v83
	v_add_f32_e32 v84, v84, v85
	v_add_f32_e32 v82, v82, v84
	v_add_f32_e32 v70, v70, v74
	v_add_f32_e32 v70, v70, v78
	v_add_f32_e32 v5, v70, v82
	v_fmamk_f32 v5, v5, 0x3a800000, v251
	v_mul_f32_e32 v6, 0x4f800000, v5
	v_cmp_gt_f32_e32 vcc, s14, v5
	s_nop 1
	v_cndmask_b32_e32 v5, v5, v6, vcc
	v_sqrt_f32_e32 v6, v5
	s_nop 0
	v_add_u32_e32 v7, -1, v6
	v_add_u32_e32 v8, 1, v6
	v_fma_f32 v9, -v7, v6, v5
	v_fma_f32 v10, -v8, v6, v5
	v_cmp_ge_f32_e64 s[34:35], 0, v9
	s_nop 1
	v_cndmask_b32_e64 v6, v6, v7, s[34:35]
	v_cmp_lt_f32_e64 s[34:35], 0, v10
	s_nop 1
	v_cndmask_b32_e64 v6, v6, v8, s[34:35]
	v_mul_f32_e32 v7, 0x37800000, v6
	v_cndmask_b32_e32 v6, v6, v7, vcc
	v_cmp_class_f32_e32 vcc, v5, v247
	s_nop 1
	v_cndmask_b32_e32 v5, v6, v5, vcc
	v_div_scale_f32 v6, s[24:25], v5, v5, 1.0
	v_rcp_f32_e32 v7, v6
	v_div_scale_f32 v8, vcc, 1.0, v5, 1.0
	v_fma_f32 v9, -v6, v7, 1.0
	v_fmac_f32_e32 v7, v9, v7
	v_mul_f32_e32 v9, v8, v7
	v_fma_f32 v10, -v6, v9, v8
	v_fmac_f32_e32 v9, v10, v7
	v_fma_f32 v6, -v6, v9, v8
	v_div_fmas_f32 v6, v6, v7, v9
	v_div_fixup_f32 v5, v6, v5, 1.0
	ds_write_b32 v4, v5 offset:6144
.Lipre_done:
.LBB0_161:
	s_ashr_i32 s24, s0, 8
	s_cmp_eq_u32 s24, 1
	s_cselect_b64 s[18:19], -1, 0
	s_cmp_lg_u32 s24, 1
	s_cbranch_scc1 .LBB0_163
	s_barrier
